# w1: next unit's phase-1 staging issued before the epilogue stores; first-iteration phase-2 vmcnt wait of follow-on units counts past the 16 stores (no in-order wait on store completion)
# speedup vs baseline: 1.0133x; 1.0067x over previous
; #define PG8_STAGE(bufoff, gbase, voff) do { _Pragma("unroll") for (int _i = 0; _i < 2; ++_i) \
;         __builtin_amdgcn_global_load_lds((const unsigned*)((const char*)(gbase) + (voff)[_i]), (LAS unsigned*)(lds + (bufoff) + ldsw + _i * 8192), 16, 0, 0); } while (0)
; #define PG8_LDA(dst, b, h) do { _Pragma("unroll") for (int m = 0; m < 4; ++m) _Pragma("unroll") for (int k = 0; k < 2; ++k) dst[m][k] = *(const LAS bf16x8*)(lds + PG8_SA(b, h) + aoff + m * 2048 + k * 1024); } while (0)
; #define PG8_LDB(dst, b, h) do { _Pragma("unroll") for (int n = 0; n < 2; ++n) _Pragma("unroll") for (int k = 0; k < 2; ++k) dst[n][k] = *(const LAS bf16x8*)(lds + PG8_SB(b, h) + boff + n * 2048 + k * 1024); } while (0)
; #define PG8_MMA(ai, bj, At, Bt) do { __builtin_amdgcn_s_setprio(1); _Pragma("unroll") for (int m = 0; m < 4; ++m) _Pragma("unroll") for (int n = 0; n < 2; ++n) _Pragma("unroll") for (int k = 0; k < 2; ++k) \
;         acc[ai][bj][m][n] = __builtin_amdgcn_mfma_f32_16x16x32_bf16(Bt[n][k], At[m][k], acc[ai][bj][m][n], 0, 0, 0); __builtin_amdgcn_s_setprio(0); } while (0)
; #define PG8_WAIT_V(n) asm volatile("s_waitcnt vmcnt(" #n ")" ::: "memory")
; #define PG8_WAIT_L(n) asm volatile("s_waitcnt lgkmcnt(" #n ")" ::: "memory")
; #define PG8_BAR __builtin_amdgcn_s_barrier()
; #define PG8_SCHED __builtin_amdgcn_sched_barrier(0)
; template <class Epi, class Sched>
; __device__ __forceinline__ void gemm_phase(LAS unsigned char* lds, const Gemm g, const Sched& S, const Epi& E) {
;     ...
;             PG8_LDB(B0, 0, 0); PG8_SCHED; PG8_LDA(At, 0, 0); PG8_STAGE(PG8_SA(1, 1), a1 + hstep, voffA);
;             PG8_WAIT_L(8); PG8_BAR; PG8_WAIT_L(0); PG8_MMA(0, 0, At, B0); PG8_BAR; PG8_SCHED;
;             PG8_LDB(B1, 0, 1); PG8_STAGE(PG8_SB(0, 0), b2, voffB);
;             PG8_BAR; PG8_WAIT_L(0); PG8_MMA(0, 1, At, B1); PG8_BAR;
;             PG8_LDA(At, 0, 1); PG8_STAGE(PG8_SA(0, 0), a2, voffA);
;             PG8_BAR; PG8_WAIT_L(0); PG8_MMA(1, 0, At, B0); PG8_BAR; PG8_SCHED;
;             PG8_STAGE(PG8_SB(0, 1), b2 + hstep, voffB);
;             PG8_WAIT_V(6); PG8_BAR; PG8_MMA(1, 1, At, B1); PG8_BAR;
.LBB0_73:
	s_add_u32 s38, s46, 0xfff80080
	s_addc_u32 s39, s47, -1
	s_cmp_eq_u32 s73, 28
	s_cselect_b32 s51, s29, s39
	s_cselect_b32 s50, s69, s38
	s_cselect_b32 s49, s27, s72
	s_cselect_b32 s48, s70, s71
	s_add_i32 m0, s9, 0xc000
	s_nop 0
	global_load_lds_dwordx4 v138, s[46:47]
	s_add_i32 m0, s9, 0xe000
	s_nop 0
	global_load_lds_dwordx4 v136, s[46:47]
	s_add_i32 s74, 0, 0x10000
	v_add_u32_e32 v140, s74, v143
	ds_read_b128 v[146:149], v140
	ds_read_b128 v[150:153], v140 offset:1024
	ds_read_b128 v[154:157], v140 offset:2048
	ds_read_b128 v[160:163], v140 offset:3072
	ds_read_b128 v[164:167], v145
	ds_read_b128 v[168:171], v145 offset:1024
	ds_read_b128 v[172:175], v145 offset:2048
	ds_read_b128 v[176:179], v145 offset:3072
	ds_read_b128 v[180:183], v145 offset:4096
	ds_read_b128 v[184:187], v145 offset:5120
	ds_read_b128 v[188:191], v145 offset:6144
	ds_read_b128 v[192:195], v145 offset:7168
	s_add_i32 s75, 0, 0x14000
	v_add_u32_e32 v140, s75, v143
	ds_read_b128 v[196:199], v140
	ds_read_b128 v[200:203], v140 offset:1024
	ds_read_b128 v[204:207], v140 offset:2048
	ds_read_b128 v[210:213], v140 offset:3072
	s_waitcnt lgkmcnt(4)
	s_barrier
	s_waitcnt lgkmcnt(0)
	v_mfma_f32_16x16x32_bf16 v[126:129], v[146:149], v[164:167], v[126:129]
	v_mfma_f32_16x16x32_bf16 v[122:125], v[154:157], v[164:167], v[122:125]
	v_mfma_f32_16x16x32_bf16 v[110:113], v[146:149], v[172:175], v[110:113]
	v_mfma_f32_16x16x32_bf16 v[106:109], v[154:157], v[172:175], v[106:109]
	v_mfma_f32_16x16x32_bf16 v[94:97], v[146:149], v[180:183], v[94:97]
	v_mfma_f32_16x16x32_bf16 v[90:93], v[154:157], v[180:183], v[90:93]
	v_mfma_f32_16x16x32_bf16 v[78:81], v[146:149], v[188:191], v[78:81]
	v_mfma_f32_16x16x32_bf16 v[74:77], v[154:157], v[188:191], v[74:77]
	v_mfma_f32_16x16x32_bf16 v[126:129], v[150:153], v[168:171], v[126:129]
	v_mfma_f32_16x16x32_bf16 v[122:125], v[160:163], v[168:171], v[122:125]
	v_mfma_f32_16x16x32_bf16 v[110:113], v[150:153], v[176:179], v[110:113]
	v_mfma_f32_16x16x32_bf16 v[106:109], v[160:163], v[176:179], v[106:109]
	v_mfma_f32_16x16x32_bf16 v[94:97], v[150:153], v[184:187], v[94:97]
	v_mfma_f32_16x16x32_bf16 v[90:93], v[160:163], v[184:187], v[90:93]
	v_mfma_f32_16x16x32_bf16 v[78:81], v[150:153], v[192:195], v[78:81]
	v_mfma_f32_16x16x32_bf16 v[74:77], v[160:163], v[192:195], v[74:77]
	v_mfma_f32_16x16x32_bf16 v[118:121], v[196:199], v[164:167], v[118:121]
	v_mfma_f32_16x16x32_bf16 v[114:117], v[204:207], v[164:167], v[114:117]
	v_mfma_f32_16x16x32_bf16 v[102:105], v[196:199], v[172:175], v[102:105]
	v_mfma_f32_16x16x32_bf16 v[98:101], v[204:207], v[172:175], v[98:101]
	v_mfma_f32_16x16x32_bf16 v[86:89], v[196:199], v[180:183], v[86:89]
	v_mfma_f32_16x16x32_bf16 v[82:85], v[204:207], v[180:183], v[82:85]
	v_mfma_f32_16x16x32_bf16 v[70:73], v[196:199], v[188:191], v[70:73]
	v_mfma_f32_16x16x32_bf16 v[66:69], v[204:207], v[188:191], v[66:69]
	v_mfma_f32_16x16x32_bf16 v[118:121], v[200:203], v[168:171], v[118:121]
	v_mfma_f32_16x16x32_bf16 v[114:117], v[210:213], v[168:171], v[114:117]
	v_mfma_f32_16x16x32_bf16 v[102:105], v[200:203], v[176:179], v[102:105]
	v_mfma_f32_16x16x32_bf16 v[98:101], v[210:213], v[176:179], v[98:101]
	v_mfma_f32_16x16x32_bf16 v[86:89], v[200:203], v[184:187], v[86:89]
	v_mfma_f32_16x16x32_bf16 v[82:85], v[210:213], v[184:187], v[82:85]
	v_mfma_f32_16x16x32_bf16 v[70:73], v[200:203], v[192:195], v[70:73]
	v_mfma_f32_16x16x32_bf16 v[66:69], v[210:213], v[192:195], v[66:69]
	s_barrier
	s_add_i32 s38, s74, s56
	s_mov_b32 m0, s38
	s_nop 0
	global_load_lds_dwordx4 v0, s[48:49]
	s_add_i32 m0, s38, 0x2000
	s_nop 0
	global_load_lds_dwordx4 v130, s[48:49]
	s_mov_b32 m0, s9
	s_nop 0
	global_load_lds_dwordx4 v134, s[50:51]
	s_mov_b32 m0, s60
	s_nop 0
	global_load_lds_dwordx4 v132, s[50:51]
	ds_read_b128 v[164:167], v145 offset:16384
	ds_read_b128 v[168:171], v145 offset:17408
	ds_read_b128 v[172:175], v145 offset:18432
	ds_read_b128 v[176:179], v145 offset:19456
	ds_read_b128 v[180:183], v145 offset:20480
	ds_read_b128 v[184:187], v145 offset:21504
	ds_read_b128 v[188:191], v145 offset:22528
	ds_read_b128 v[192:195], v145 offset:23552
	s_cmp_lg_u32 s73, -2
	s_cbranch_scc1 .Lq2n_73
	s_cmp_eq_u32 s67, 1
	s_cbranch_scc1 .Lq2n_73
	s_waitcnt vmcnt(22)
	s_branch .Lq2d_73
.Lq2n_73:
	s_waitcnt vmcnt(4)
; #define PG8_STAGE(bufoff, gbase, voff) do { _Pragma("unroll") for (int _i = 0; _i < 2; ++_i) \
;         __builtin_amdgcn_global_load_lds((const unsigned*)((const char*)(gbase) + (voff)[_i]), (LAS unsigned*)(lds + (bufoff) + ldsw + _i * 8192), 16, 0, 0); } while (0)
; #define PG8_LDA(dst, b, h) do { _Pragma("unroll") for (int m = 0; m < 4; ++m) _Pragma("unroll") for (int k = 0; k < 2; ++k) dst[m][k] = *(const LAS bf16x8*)(lds + PG8_SA(b, h) + aoff + m * 2048 + k * 1024); } while (0)
; #define PG8_LDB(dst, b, h) do { _Pragma("unroll") for (int n = 0; n < 2; ++n) _Pragma("unroll") for (int k = 0; k < 2; ++k) dst[n][k] = *(const LAS bf16x8*)(lds + PG8_SB(b, h) + boff + n * 2048 + k * 1024); } while (0)
; #define PG8_MMA(ai, bj, At, Bt) do { __builtin_amdgcn_s_setprio(1); _Pragma("unroll") for (int m = 0; m < 4; ++m) _Pragma("unroll") for (int n = 0; n < 2; ++n) _Pragma("unroll") for (int k = 0; k < 2; ++k) \
;         acc[ai][bj][m][n] = __builtin_amdgcn_mfma_f32_16x16x32_bf16(Bt[n][k], At[m][k], acc[ai][bj][m][n], 0, 0, 0); __builtin_amdgcn_s_setprio(0); } while (0)
; #define PG8_WAIT_V(n) asm volatile("s_waitcnt vmcnt(" #n ")" ::: "memory")
; #define PG8_WAIT_L(n) asm volatile("s_waitcnt lgkmcnt(" #n ")" ::: "memory")
; #define PG8_BAR __builtin_amdgcn_s_barrier()
; #define PG8_SCHED __builtin_amdgcn_sched_barrier(0)
; template <class Epi, class Sched>
; __device__ __forceinline__ void gemm_phase(LAS unsigned char* lds, const Gemm g, const Sched& S, const Epi& E) {
;     ...
;             PG8_BAR; PG8_WAIT_L(0); PG8_MMA(1, 0, At, B0); PG8_BAR; PG8_SCHED;
;             PG8_STAGE(PG8_SB(0, 1), b2 + hstep, voffB);
;             PG8_WAIT_V(6); PG8_BAR; PG8_MMA(1, 1, At, B1); PG8_BAR;
;             PG8_LDB(B0, 1, 0); PG8_SCHED; PG8_LDA(At, 1, 0); PG8_STAGE(PG8_SA(0, 1), a2 + hstep, voffA);
;             PG8_WAIT_L(8); PG8_BAR; PG8_WAIT_L(0); PG8_MMA(0, 0, At, B0); PG8_BAR; PG8_SCHED;
;             PG8_LDB(B1, 1, 1); PG8_STAGE(PG8_SB(1, 0), b3, voffB);
;             PG8_BAR; PG8_WAIT_L(0); PG8_MMA(0, 1, At, B1); PG8_BAR;
.Lq2d_73:
	s_waitcnt lgkmcnt(0)
	s_barrier
	v_mfma_f32_16x16x32_bf16 v[62:65], v[146:149], v[164:167], v[62:65]
	v_mfma_f32_16x16x32_bf16 v[58:61], v[154:157], v[164:167], v[58:61]
	v_mfma_f32_16x16x32_bf16 v[46:49], v[146:149], v[172:175], v[46:49]
	v_mfma_f32_16x16x32_bf16 v[42:45], v[154:157], v[172:175], v[42:45]
	v_mfma_f32_16x16x32_bf16 v[30:33], v[146:149], v[180:183], v[30:33]
	v_mfma_f32_16x16x32_bf16 v[26:29], v[154:157], v[180:183], v[26:29]
	v_mfma_f32_16x16x32_bf16 v[14:17], v[146:149], v[188:191], v[14:17]
	v_mfma_f32_16x16x32_bf16 v[10:13], v[154:157], v[188:191], v[10:13]
	v_mfma_f32_16x16x32_bf16 v[62:65], v[150:153], v[168:171], v[62:65]
	v_mfma_f32_16x16x32_bf16 v[58:61], v[160:163], v[168:171], v[58:61]
	v_mfma_f32_16x16x32_bf16 v[46:49], v[150:153], v[176:179], v[46:49]
	v_mfma_f32_16x16x32_bf16 v[42:45], v[160:163], v[176:179], v[42:45]
	v_mfma_f32_16x16x32_bf16 v[30:33], v[150:153], v[184:187], v[30:33]
	v_mfma_f32_16x16x32_bf16 v[26:29], v[160:163], v[184:187], v[26:29]
	v_mfma_f32_16x16x32_bf16 v[14:17], v[150:153], v[192:195], v[14:17]
	v_mfma_f32_16x16x32_bf16 v[10:13], v[160:163], v[192:195], v[10:13]
	v_mfma_f32_16x16x32_bf16 v[54:57], v[196:199], v[164:167], v[54:57]
	v_mfma_f32_16x16x32_bf16 v[50:53], v[204:207], v[164:167], v[50:53]
	v_mfma_f32_16x16x32_bf16 v[38:41], v[196:199], v[172:175], v[38:41]
	v_mfma_f32_16x16x32_bf16 v[34:37], v[204:207], v[172:175], v[34:37]
	v_mfma_f32_16x16x32_bf16 v[22:25], v[196:199], v[180:183], v[22:25]
	v_mfma_f32_16x16x32_bf16 v[18:21], v[204:207], v[180:183], v[18:21]
	v_mfma_f32_16x16x32_bf16 v[6:9], v[196:199], v[188:191], v[6:9]
	v_mfma_f32_16x16x32_bf16 v[2:5], v[204:207], v[188:191], v[2:5]
	v_mfma_f32_16x16x32_bf16 v[54:57], v[200:203], v[168:171], v[54:57]
	v_mfma_f32_16x16x32_bf16 v[50:53], v[210:213], v[168:171], v[50:53]
	v_mfma_f32_16x16x32_bf16 v[38:41], v[200:203], v[176:179], v[38:41]
	v_mfma_f32_16x16x32_bf16 v[34:37], v[210:213], v[176:179], v[34:37]
	v_mfma_f32_16x16x32_bf16 v[22:25], v[200:203], v[184:187], v[22:25]
	v_mfma_f32_16x16x32_bf16 v[18:21], v[210:213], v[184:187], v[18:21]
	v_mfma_f32_16x16x32_bf16 v[6:9], v[200:203], v[192:195], v[6:9]
	v_mfma_f32_16x16x32_bf16 v[2:5], v[210:213], v[192:195], v[2:5]
	s_barrier
	s_add_u32 s38, s48, 0x80000
	s_addc_u32 s39, s49, 0
	s_add_i32 s74, s75, s56
	s_mov_b32 m0, s74
	s_nop 0
	global_load_lds_dwordx4 v0, s[38:39]
	s_add_i32 m0, s74, 0x2000
	s_nop 0
	global_load_lds_dwordx4 v130, s[38:39]
	s_add_u32 s38, s50, 0x80000
	s_addc_u32 s39, s51, 0
	s_mov_b32 m0, s61
	s_nop 0
	global_load_lds_dwordx4 v134, s[38:39]
	s_mov_b32 m0, s62
	s_nop 0
	global_load_lds_dwordx4 v132, s[38:39]
	s_add_i32 s74, 0, 0x18000
	v_add_u32_e32 v160, s74, v143
	ds_read_b128 v[146:149], v160
	ds_read_b128 v[150:153], v160 offset:1024
	ds_read_b128 v[154:157], v160 offset:2048
	ds_read_b128 v[160:163], v160 offset:3072
	ds_read_b128 v[164:167], v145 offset:32768
	ds_read_b128 v[168:171], v145 offset:33792
	ds_read_b128 v[172:175], v145 offset:34816
	ds_read_b128 v[176:179], v145 offset:35840
	ds_read_b128 v[180:183], v145 offset:36864
	ds_read_b128 v[184:187], v145 offset:37888
	ds_read_b128 v[188:191], v145 offset:38912
	ds_read_b128 v[192:195], v145 offset:39936
	s_nop 0
	v_add_u32_e32 v210, 0x1c000, v143
	ds_read_b128 v[196:199], v210
	ds_read_b128 v[200:203], v210 offset:1024
	ds_read_b128 v[204:207], v210 offset:2048
	ds_read_b128 v[210:213], v210 offset:3072
	s_waitcnt lgkmcnt(4)
	s_barrier
	s_waitcnt lgkmcnt(0)
	v_mfma_f32_16x16x32_bf16 v[126:129], v[146:149], v[164:167], v[126:129]
	v_mfma_f32_16x16x32_bf16 v[122:125], v[154:157], v[164:167], v[122:125]
	v_mfma_f32_16x16x32_bf16 v[110:113], v[146:149], v[172:175], v[110:113]
	v_mfma_f32_16x16x32_bf16 v[106:109], v[154:157], v[172:175], v[106:109]
	v_mfma_f32_16x16x32_bf16 v[94:97], v[146:149], v[180:183], v[94:97]
	v_mfma_f32_16x16x32_bf16 v[90:93], v[154:157], v[180:183], v[90:93]
	v_mfma_f32_16x16x32_bf16 v[78:81], v[146:149], v[188:191], v[78:81]
	v_mfma_f32_16x16x32_bf16 v[74:77], v[154:157], v[188:191], v[74:77]
	v_mfma_f32_16x16x32_bf16 v[126:129], v[150:153], v[168:171], v[126:129]
	v_mfma_f32_16x16x32_bf16 v[122:125], v[160:163], v[168:171], v[122:125]
	v_mfma_f32_16x16x32_bf16 v[110:113], v[150:153], v[176:179], v[110:113]
	v_mfma_f32_16x16x32_bf16 v[106:109], v[160:163], v[176:179], v[106:109]
	v_mfma_f32_16x16x32_bf16 v[94:97], v[150:153], v[184:187], v[94:97]
	v_mfma_f32_16x16x32_bf16 v[90:93], v[160:163], v[184:187], v[90:93]
	v_mfma_f32_16x16x32_bf16 v[78:81], v[150:153], v[192:195], v[78:81]
	v_mfma_f32_16x16x32_bf16 v[74:77], v[160:163], v[192:195], v[74:77]
	v_mfma_f32_16x16x32_bf16 v[118:121], v[196:199], v[164:167], v[118:121]
	v_mfma_f32_16x16x32_bf16 v[114:117], v[204:207], v[164:167], v[114:117]
	v_mfma_f32_16x16x32_bf16 v[102:105], v[196:199], v[172:175], v[102:105]
	v_mfma_f32_16x16x32_bf16 v[98:101], v[204:207], v[172:175], v[98:101]
	v_mfma_f32_16x16x32_bf16 v[86:89], v[196:199], v[180:183], v[86:89]
	v_mfma_f32_16x16x32_bf16 v[82:85], v[204:207], v[180:183], v[82:85]
	v_mfma_f32_16x16x32_bf16 v[70:73], v[196:199], v[188:191], v[70:73]
	v_mfma_f32_16x16x32_bf16 v[66:69], v[204:207], v[188:191], v[66:69]
	v_mfma_f32_16x16x32_bf16 v[118:121], v[200:203], v[168:171], v[118:121]
	v_mfma_f32_16x16x32_bf16 v[114:117], v[210:213], v[168:171], v[114:117]
	v_mfma_f32_16x16x32_bf16 v[102:105], v[200:203], v[176:179], v[102:105]
	v_mfma_f32_16x16x32_bf16 v[98:101], v[210:213], v[176:179], v[98:101]
	v_mfma_f32_16x16x32_bf16 v[86:89], v[200:203], v[184:187], v[86:89]
	v_mfma_f32_16x16x32_bf16 v[82:85], v[210:213], v[184:187], v[82:85]
	v_mfma_f32_16x16x32_bf16 v[70:73], v[200:203], v[192:195], v[70:73]
	v_mfma_f32_16x16x32_bf16 v[66:69], v[210:213], v[192:195], v[66:69]
	s_barrier
; #define PG8_STAGE(bufoff, gbase, voff) do { _Pragma("unroll") for (int _i = 0; _i < 2; ++_i) \
;         __builtin_amdgcn_global_load_lds((const unsigned*)((const char*)(gbase) + (voff)[_i]), (LAS unsigned*)(lds + (bufoff) + ldsw + _i * 8192), 16, 0, 0); } while (0)
; #define PG8_LDA(dst, b, h) do { _Pragma("unroll") for (int m = 0; m < 4; ++m) _Pragma("unroll") for (int k = 0; k < 2; ++k) dst[m][k] = *(const LAS bf16x8*)(lds + PG8_SA(b, h) + aoff + m * 2048 + k * 1024); } while (0)
; #define PG8_LDB(dst, b, h) do { _Pragma("unroll") for (int n = 0; n < 2; ++n) _Pragma("unroll") for (int k = 0; k < 2; ++k) dst[n][k] = *(const LAS bf16x8*)(lds + PG8_SB(b, h) + boff + n * 2048 + k * 1024); } while (0)
; #define PG8_MMA(ai, bj, At, Bt) do { __builtin_amdgcn_s_setprio(1); _Pragma("unroll") for (int m = 0; m < 4; ++m) _Pragma("unroll") for (int n = 0; n < 2; ++n) _Pragma("unroll") for (int k = 0; k < 2; ++k) \
;         acc[ai][bj][m][n] = __builtin_amdgcn_mfma_f32_16x16x32_bf16(Bt[n][k], At[m][k], acc[ai][bj][m][n], 0, 0, 0); __builtin_amdgcn_s_setprio(0); } while (0)
; #define PG8_WAIT_V(n) asm volatile("s_waitcnt vmcnt(" #n ")" ::: "memory")
; #define PG8_WAIT_L(n) asm volatile("s_waitcnt lgkmcnt(" #n ")" ::: "memory")
; #define PG8_BAR __builtin_amdgcn_s_barrier()
; #define PG8_SCHED __builtin_amdgcn_sched_barrier(0)
; template <class Epi, class Sched>
; __device__ __forceinline__ void gemm_phase(LAS unsigned char* lds, const Gemm g, const Sched& S, const Epi& E) {
;     ...
;             PG8_WAIT_V(6); PG8_BAR; PG8_MMA(1, 1, At, B1); PG8_BAR;
;             PG8_LDB(B0, 1, 0); PG8_SCHED; PG8_LDA(At, 1, 0); PG8_STAGE(PG8_SA(0, 1), a2 + hstep, voffA);
;             PG8_WAIT_L(8); PG8_BAR; PG8_WAIT_L(0); PG8_MMA(0, 0, At, B0); PG8_BAR; PG8_SCHED;
;             PG8_LDB(B1, 1, 1); PG8_STAGE(PG8_SB(1, 0), b3, voffB);
;             PG8_BAR; PG8_WAIT_L(0); PG8_MMA(0, 1, At, B1); PG8_BAR;
;             PG8_LDA(At, 1, 1); PG8_STAGE(PG8_SA(1, 0), a3, voffA);
;             PG8_BAR; PG8_WAIT_L(0); PG8_MMA(1, 0, At, B0); PG8_BAR; PG8_SCHED;
;             PG8_STAGE(PG8_SB(1, 1), b3 + hstep, voffB);
;             PG8_WAIT_V(6); PG8_BAR; PG8_MMA(1, 1, At, B1); PG8_BAR;
;         }
;         E(acc, cur, wr, wc, fr, fq);
;         if (!has_next) break;
	s_add_i32 s38, s74, s56
	s_add_u32 s100, s48, s36
	s_addc_u32 s101, s49, s37
	s_mov_b32 m0, s38
	s_nop 0
	global_load_lds_dwordx4 v0, s[100:101]
	s_add_i32 m0, s38, 0x2000
	s_nop 0
	global_load_lds_dwordx4 v130, s[100:101]
	s_mov_b32 m0, s64
	s_add_u32 s100, s50, s36
	s_addc_u32 s101, s51, s37
	global_load_lds_dwordx4 v134, s[100:101]
	s_mov_b32 m0, s65
	s_nop 0
	global_load_lds_dwordx4 v132, s[100:101]
	ds_read_b128 v[164:167], v145 offset:49152
	ds_read_b128 v[168:171], v145 offset:50176
	ds_read_b128 v[172:175], v145 offset:51200
	ds_read_b128 v[176:179], v145 offset:52224
	ds_read_b128 v[180:183], v145 offset:53248
	ds_read_b128 v[184:187], v145 offset:54272
	ds_read_b128 v[188:191], v145 offset:55296
	ds_read_b128 v[192:195], v145 offset:56320
	s_waitcnt vmcnt(4)
	s_waitcnt lgkmcnt(0)
	s_barrier
	v_mfma_f32_16x16x32_bf16 v[62:65], v[146:149], v[164:167], v[62:65]
	v_mfma_f32_16x16x32_bf16 v[58:61], v[154:157], v[164:167], v[58:61]
	v_mfma_f32_16x16x32_bf16 v[46:49], v[146:149], v[172:175], v[46:49]
	v_mfma_f32_16x16x32_bf16 v[42:45], v[154:157], v[172:175], v[42:45]
	v_mfma_f32_16x16x32_bf16 v[30:33], v[146:149], v[180:183], v[30:33]
	v_mfma_f32_16x16x32_bf16 v[26:29], v[154:157], v[180:183], v[26:29]
	v_mfma_f32_16x16x32_bf16 v[14:17], v[146:149], v[188:191], v[14:17]
	v_mfma_f32_16x16x32_bf16 v[10:13], v[154:157], v[188:191], v[10:13]
	v_mfma_f32_16x16x32_bf16 v[62:65], v[150:153], v[168:171], v[62:65]
	v_mfma_f32_16x16x32_bf16 v[58:61], v[160:163], v[168:171], v[58:61]
	v_mfma_f32_16x16x32_bf16 v[46:49], v[150:153], v[176:179], v[46:49]
	v_mfma_f32_16x16x32_bf16 v[42:45], v[160:163], v[176:179], v[42:45]
	v_mfma_f32_16x16x32_bf16 v[30:33], v[150:153], v[184:187], v[30:33]
	v_mfma_f32_16x16x32_bf16 v[26:29], v[160:163], v[184:187], v[26:29]
	v_mfma_f32_16x16x32_bf16 v[14:17], v[150:153], v[192:195], v[14:17]
	v_mfma_f32_16x16x32_bf16 v[10:13], v[160:163], v[192:195], v[10:13]
	s_add_u32 s38, s48, 0x80080
	s_addc_u32 s39, s49, 0
	s_add_i32 s48, s56, 0x1c000
	s_mov_b32 m0, s48
	s_nop 0
	global_load_lds_dwordx4 v0, s[38:39]
	s_add_i32 m0, s48, 0x2000
	s_nop 0
	global_load_lds_dwordx4 v130, s[38:39]
	v_mfma_f32_16x16x32_bf16 v[54:57], v[196:199], v[164:167], v[54:57]
	v_mfma_f32_16x16x32_bf16 v[50:53], v[204:207], v[164:167], v[50:53]
	v_mfma_f32_16x16x32_bf16 v[38:41], v[196:199], v[172:175], v[38:41]
	v_mfma_f32_16x16x32_bf16 v[34:37], v[204:207], v[172:175], v[34:37]
	v_mfma_f32_16x16x32_bf16 v[22:25], v[196:199], v[180:183], v[22:25]
	v_mfma_f32_16x16x32_bf16 v[18:21], v[204:207], v[180:183], v[18:21]
	v_mfma_f32_16x16x32_bf16 v[6:9], v[196:199], v[188:191], v[6:9]
	v_mfma_f32_16x16x32_bf16 v[2:5], v[204:207], v[188:191], v[2:5]
	v_mfma_f32_16x16x32_bf16 v[54:57], v[200:203], v[168:171], v[54:57]
	v_mfma_f32_16x16x32_bf16 v[50:53], v[210:213], v[168:171], v[50:53]
	v_mfma_f32_16x16x32_bf16 v[38:41], v[200:203], v[176:179], v[38:41]
	v_mfma_f32_16x16x32_bf16 v[34:37], v[210:213], v[176:179], v[34:37]
	v_mfma_f32_16x16x32_bf16 v[22:25], v[200:203], v[184:187], v[22:25]
	v_mfma_f32_16x16x32_bf16 v[18:21], v[210:213], v[184:187], v[18:21]
	v_mfma_f32_16x16x32_bf16 v[6:9], v[200:203], v[192:195], v[6:9]
	v_mfma_f32_16x16x32_bf16 v[2:5], v[210:213], v[192:195], v[2:5]
	s_add_i32 s73, s73, 2
	s_add_u32 s71, s71, 0x100
	s_addc_u32 s72, s72, 0
	s_add_u32 s46, s46, 0x100
	s_addc_u32 s47, s47, 0
	s_cmp_gt_u32 s73, 29
	s_barrier
	s_cbranch_scc0 .LBB0_73
	s_cmp_lg_u64 s[40:41], 0
	s_cbranch_scc1 .Lnoh_73
	s_add_u32 s100, s42, 0x80080
	s_addc_u32 s101, s43, 0
	s_add_i32 m0, s9, 0xc000
	s_nop 0
	global_load_lds_dwordx4 v138, s[100:101]
	s_add_i32 m0, s9, 0xe000
	s_nop 0
	global_load_lds_dwordx4 v136, s[100:101]
